# P1 merge-gate (sig8) epilogue rewritten by hand: packed f32 mul/fma/add, 255 folded into the reciprocal, round-to-nearest-even by adding 2^23; single copy
# speedup vs baseline: 1.0023x; 1.0023x over previous
.LBB0_127:
	s_cmp_gt_i32 s33, 0
	s_cselect_b64 s[2:3], -1, 0
	s_and_b64 s[44:45], s[2:3], exec
	s_cselect_b32 s4, 0x80, 0
	s_add_i32 s4, s43, s4
	v_add_u32_e32 v5, s4, v3
	s_cmp_gt_u32 s72, 11
	s_mov_b64 s[76:77], -1
	s_cbranch_scc0 .LBB0_159
	s_cmp_gt_u32 s72, 15
	s_cbranch_scc0 .LBB0_156
	s_cmp_gt_u32 s72, 19
	s_cbranch_scc0 .LBB0_153
	s_cmp_lt_i32 s72, 21
	s_cbranch_scc1 .LBB0_150
	s_cmp_lg_u32 s72, 21
	s_cbranch_scc0 .LBB0_147
	s_cmp_gt_u32 s72, 25
	s_cbranch_scc0 .LBB0_144
	s_mov_b32 s84, 0xbfb8aa3b
	s_mov_b32 s85, s84
	s_mov_b32 s86, 0x3b808081
	s_mov_b32 s87, s86
	s_mov_b32 s88, 0x4b000000
	s_mov_b32 s89, s88
	s_mov_b32 s90, 0x06050400
	s_lshl_b32 s63, s72, 3
	s_lshl_b32 s36, s74, 5
	s_cmp_gt_i32 s33, 0
	s_cselect_b32 s4, 0x1000, 0
	v_lshlrev_b32_e32 v134, 3, v231
	v_lshl_add_u32 v134, v226, 7, v134
	v_ashrrev_i32_e32 v135, 31, v134
	s_cmp_gt_u32 s72, 29
	s_cbranch_scc0 .Lsig8_lo
	v_readlane_b32 s2, v254, 37
	v_readlane_b32 s44, v254, 45
	v_readlane_b32 s45, v254, 47
	s_branch .Lsig8_go
.Lsig8_lo:
	v_readlane_b32 s2, v254, 39
	v_readlane_b32 s44, v254, 20
	v_readlane_b32 s45, v254, 21
.Lsig8_go:
	s_add_i32 s2, s2, s63
	s_add_i32 s2, s2, s36
	s_ashr_i32 s3, s2, 31
	s_lshl_b64 s[2:3], s[2:3], 13
	s_add_u32 s2, s44, s2
	s_addc_u32 s3, s45, s3
	v_lshl_add_u64 v[144:145], s[2:3], 0, v[134:135]
	v_lshl_add_u64 v[144:145], v[144:145], 0, s[4:5]
	v_pk_mul_f32 v[150:151], v[102:103], s[84:85] op_sel_hi:[1,0]
	v_pk_mul_f32 v[152:153], v[104:105], s[84:85] op_sel_hi:[1,0]
	v_pk_mul_f32 v[154:155], v[70:71], s[84:85] op_sel_hi:[1,0]
	v_pk_mul_f32 v[156:157], v[72:73], s[84:85] op_sel_hi:[1,0]
	v_exp_f32_e32 v150, v150
	v_exp_f32_e32 v151, v151
	v_exp_f32_e32 v152, v152
	v_exp_f32_e32 v153, v153
	v_exp_f32_e32 v154, v154
	v_exp_f32_e32 v155, v155
	v_exp_f32_e32 v156, v156
	v_exp_f32_e32 v157, v157
	v_pk_fma_f32 v[150:151], v[150:151], s[86:87], s[86:87] op_sel_hi:[1,0,0]
	v_pk_fma_f32 v[152:153], v[152:153], s[86:87], s[86:87] op_sel_hi:[1,0,0]
	v_pk_fma_f32 v[154:155], v[154:155], s[86:87], s[86:87] op_sel_hi:[1,0,0]
	v_pk_fma_f32 v[156:157], v[156:157], s[86:87], s[86:87] op_sel_hi:[1,0,0]
	v_rcp_f32_e32 v150, v150
	v_rcp_f32_e32 v151, v151
	v_rcp_f32_e32 v152, v152
	v_rcp_f32_e32 v153, v153
	v_rcp_f32_e32 v154, v154
	v_rcp_f32_e32 v155, v155
	v_rcp_f32_e32 v156, v156
	v_rcp_f32_e32 v157, v157
	v_max_f32_e32 v150, 1.0, v150
	v_max_f32_e32 v151, 1.0, v151
	v_max_f32_e32 v152, 1.0, v152
	v_max_f32_e32 v153, 1.0, v153
	v_max_f32_e32 v154, 1.0, v154
	v_max_f32_e32 v155, 1.0, v155
	v_max_f32_e32 v156, 1.0, v156
	v_max_f32_e32 v157, 1.0, v157
	v_pk_add_f32 v[150:151], v[150:151], s[88:89] op_sel_hi:[1,0]
	v_pk_add_f32 v[152:153], v[152:153], s[88:89] op_sel_hi:[1,0]
	v_pk_add_f32 v[154:155], v[154:155], s[88:89] op_sel_hi:[1,0]
	v_pk_add_f32 v[156:157], v[156:157], s[88:89] op_sel_hi:[1,0]
	v_lshl_or_b32 v158, v153, 8, v152
	v_lshl_or_b32 v158, v158, 8, v151
	v_perm_b32 v160, v158, v150, s90
	v_lshl_or_b32 v158, v157, 8, v156
	v_lshl_or_b32 v158, v158, 8, v155
	v_perm_b32 v161, v158, v154, s90
	global_store_dwordx2 v[144:145], v[160:161], off nt
	v_pk_mul_f32 v[162:163], v[114:115], s[84:85] op_sel_hi:[1,0]
	v_pk_mul_f32 v[164:165], v[116:117], s[84:85] op_sel_hi:[1,0]
	v_pk_mul_f32 v[166:167], v[82:83], s[84:85] op_sel_hi:[1,0]
	v_pk_mul_f32 v[168:169], v[84:85], s[84:85] op_sel_hi:[1,0]
	v_exp_f32_e32 v162, v162
	v_exp_f32_e32 v163, v163
	v_exp_f32_e32 v164, v164
	v_exp_f32_e32 v165, v165
	v_exp_f32_e32 v166, v166
	v_exp_f32_e32 v167, v167
	v_exp_f32_e32 v168, v168
	v_exp_f32_e32 v169, v169
	v_pk_fma_f32 v[162:163], v[162:163], s[86:87], s[86:87] op_sel_hi:[1,0,0]
	v_pk_fma_f32 v[164:165], v[164:165], s[86:87], s[86:87] op_sel_hi:[1,0,0]
	v_pk_fma_f32 v[166:167], v[166:167], s[86:87], s[86:87] op_sel_hi:[1,0,0]
	v_pk_fma_f32 v[168:169], v[168:169], s[86:87], s[86:87] op_sel_hi:[1,0,0]
	v_rcp_f32_e32 v162, v162
	v_rcp_f32_e32 v163, v163
	v_rcp_f32_e32 v164, v164
	v_rcp_f32_e32 v165, v165
	v_rcp_f32_e32 v166, v166
	v_rcp_f32_e32 v167, v167
	v_rcp_f32_e32 v168, v168
	v_rcp_f32_e32 v169, v169
	v_max_f32_e32 v162, 1.0, v162
	v_max_f32_e32 v163, 1.0, v163
	v_max_f32_e32 v164, 1.0, v164
	v_max_f32_e32 v165, 1.0, v165
	v_max_f32_e32 v166, 1.0, v166
	v_max_f32_e32 v167, 1.0, v167
	v_max_f32_e32 v168, 1.0, v168
	v_max_f32_e32 v169, 1.0, v169
	v_pk_add_f32 v[162:163], v[162:163], s[88:89] op_sel_hi:[1,0]
	v_pk_add_f32 v[164:165], v[164:165], s[88:89] op_sel_hi:[1,0]
	v_pk_add_f32 v[166:167], v[166:167], s[88:89] op_sel_hi:[1,0]
	v_pk_add_f32 v[168:169], v[168:169], s[88:89] op_sel_hi:[1,0]
	v_lshl_or_b32 v170, v165, 8, v164
	v_lshl_or_b32 v170, v170, 8, v163
	v_perm_b32 v172, v170, v162, s90
	v_lshl_or_b32 v170, v169, 8, v168
	v_lshl_or_b32 v170, v170, 8, v167
	v_perm_b32 v173, v170, v166, s90
	global_store_dwordx2 v[144:145], v[172:173], off offset:1024 nt
	v_pk_mul_f32 v[150:151], v[110:111], s[84:85] op_sel_hi:[1,0]
	v_pk_mul_f32 v[152:153], v[112:113], s[84:85] op_sel_hi:[1,0]
	v_pk_mul_f32 v[154:155], v[78:79], s[84:85] op_sel_hi:[1,0]
	v_pk_mul_f32 v[156:157], v[80:81], s[84:85] op_sel_hi:[1,0]
	v_exp_f32_e32 v150, v150
	v_exp_f32_e32 v151, v151
	v_exp_f32_e32 v152, v152
	v_exp_f32_e32 v153, v153
	v_exp_f32_e32 v154, v154
	v_exp_f32_e32 v155, v155
	v_exp_f32_e32 v156, v156
	v_exp_f32_e32 v157, v157
	v_pk_fma_f32 v[150:151], v[150:151], s[86:87], s[86:87] op_sel_hi:[1,0,0]
	v_pk_fma_f32 v[152:153], v[152:153], s[86:87], s[86:87] op_sel_hi:[1,0,0]
	v_pk_fma_f32 v[154:155], v[154:155], s[86:87], s[86:87] op_sel_hi:[1,0,0]
	v_pk_fma_f32 v[156:157], v[156:157], s[86:87], s[86:87] op_sel_hi:[1,0,0]
	v_rcp_f32_e32 v150, v150
	v_rcp_f32_e32 v151, v151
	v_rcp_f32_e32 v152, v152
	v_rcp_f32_e32 v153, v153
	v_rcp_f32_e32 v154, v154
	v_rcp_f32_e32 v155, v155
	v_rcp_f32_e32 v156, v156
	v_rcp_f32_e32 v157, v157
	v_max_f32_e32 v150, 1.0, v150
	v_max_f32_e32 v151, 1.0, v151
	v_max_f32_e32 v152, 1.0, v152
	v_max_f32_e32 v153, 1.0, v153
	v_max_f32_e32 v154, 1.0, v154
	v_max_f32_e32 v155, 1.0, v155
	v_max_f32_e32 v156, 1.0, v156
	v_max_f32_e32 v157, 1.0, v157
	v_pk_add_f32 v[150:151], v[150:151], s[88:89] op_sel_hi:[1,0]
	v_pk_add_f32 v[152:153], v[152:153], s[88:89] op_sel_hi:[1,0]
	v_pk_add_f32 v[154:155], v[154:155], s[88:89] op_sel_hi:[1,0]
	v_pk_add_f32 v[156:157], v[156:157], s[88:89] op_sel_hi:[1,0]
	v_lshl_or_b32 v158, v153, 8, v152
	v_lshl_or_b32 v158, v158, 8, v151
	v_perm_b32 v160, v158, v150, s90
	v_lshl_or_b32 v158, v157, 8, v156
	v_lshl_or_b32 v158, v158, 8, v155
	v_perm_b32 v161, v158, v154, s90
	global_store_dwordx2 v[144:145], v[160:161], off offset:2048 nt
	v_pk_mul_f32 v[162:163], v[106:107], s[84:85] op_sel_hi:[1,0]
	v_pk_mul_f32 v[164:165], v[108:109], s[84:85] op_sel_hi:[1,0]
	v_pk_mul_f32 v[166:167], v[74:75], s[84:85] op_sel_hi:[1,0]
	v_pk_mul_f32 v[168:169], v[76:77], s[84:85] op_sel_hi:[1,0]
	v_exp_f32_e32 v162, v162
	v_exp_f32_e32 v163, v163
	v_exp_f32_e32 v164, v164
	v_exp_f32_e32 v165, v165
	v_exp_f32_e32 v166, v166
	v_exp_f32_e32 v167, v167
	v_exp_f32_e32 v168, v168
	v_exp_f32_e32 v169, v169
	v_pk_fma_f32 v[162:163], v[162:163], s[86:87], s[86:87] op_sel_hi:[1,0,0]
	v_pk_fma_f32 v[164:165], v[164:165], s[86:87], s[86:87] op_sel_hi:[1,0,0]
	v_pk_fma_f32 v[166:167], v[166:167], s[86:87], s[86:87] op_sel_hi:[1,0,0]
	v_pk_fma_f32 v[168:169], v[168:169], s[86:87], s[86:87] op_sel_hi:[1,0,0]
	v_rcp_f32_e32 v162, v162
	v_rcp_f32_e32 v163, v163
	v_rcp_f32_e32 v164, v164
	v_rcp_f32_e32 v165, v165
	v_rcp_f32_e32 v166, v166
	v_rcp_f32_e32 v167, v167
	v_rcp_f32_e32 v168, v168
	v_rcp_f32_e32 v169, v169
	v_max_f32_e32 v162, 1.0, v162
	v_max_f32_e32 v163, 1.0, v163
	v_max_f32_e32 v164, 1.0, v164
	v_max_f32_e32 v165, 1.0, v165
	v_max_f32_e32 v166, 1.0, v166
	v_max_f32_e32 v167, 1.0, v167
	v_max_f32_e32 v168, 1.0, v168
	v_max_f32_e32 v169, 1.0, v169
	v_pk_add_f32 v[162:163], v[162:163], s[88:89] op_sel_hi:[1,0]
	v_pk_add_f32 v[164:165], v[164:165], s[88:89] op_sel_hi:[1,0]
	v_pk_add_f32 v[166:167], v[166:167], s[88:89] op_sel_hi:[1,0]
	v_pk_add_f32 v[168:169], v[168:169], s[88:89] op_sel_hi:[1,0]
	v_lshl_or_b32 v170, v165, 8, v164
	v_lshl_or_b32 v170, v170, 8, v163
	v_perm_b32 v172, v170, v162, s90
	v_lshl_or_b32 v170, v169, 8, v168
	v_lshl_or_b32 v170, v170, 8, v167
	v_perm_b32 v173, v170, v166, s90
	global_store_dwordx2 v[144:145], v[172:173], off offset:3072 nt
	v_pk_mul_f32 v[150:151], v[130:131], s[84:85] op_sel_hi:[1,0]
	v_pk_mul_f32 v[152:153], v[132:133], s[84:85] op_sel_hi:[1,0]
	v_pk_mul_f32 v[154:155], v[98:99], s[84:85] op_sel_hi:[1,0]
	v_pk_mul_f32 v[156:157], v[100:101], s[84:85] op_sel_hi:[1,0]
	v_exp_f32_e32 v150, v150
	v_exp_f32_e32 v151, v151
	v_exp_f32_e32 v152, v152
	v_exp_f32_e32 v153, v153
	v_exp_f32_e32 v154, v154
	v_exp_f32_e32 v155, v155
	v_exp_f32_e32 v156, v156
	v_exp_f32_e32 v157, v157
	v_pk_fma_f32 v[150:151], v[150:151], s[86:87], s[86:87] op_sel_hi:[1,0,0]
	v_pk_fma_f32 v[152:153], v[152:153], s[86:87], s[86:87] op_sel_hi:[1,0,0]
	v_pk_fma_f32 v[154:155], v[154:155], s[86:87], s[86:87] op_sel_hi:[1,0,0]
	v_pk_fma_f32 v[156:157], v[156:157], s[86:87], s[86:87] op_sel_hi:[1,0,0]
	v_rcp_f32_e32 v150, v150
	v_rcp_f32_e32 v151, v151
	v_rcp_f32_e32 v152, v152
	v_rcp_f32_e32 v153, v153
	v_rcp_f32_e32 v154, v154
	v_rcp_f32_e32 v155, v155
	v_rcp_f32_e32 v156, v156
	v_rcp_f32_e32 v157, v157
	v_max_f32_e32 v150, 1.0, v150
	v_max_f32_e32 v151, 1.0, v151
	v_max_f32_e32 v152, 1.0, v152
	v_max_f32_e32 v153, 1.0, v153
	v_max_f32_e32 v154, 1.0, v154
	v_max_f32_e32 v155, 1.0, v155
	v_max_f32_e32 v156, 1.0, v156
	v_max_f32_e32 v157, 1.0, v157
	v_pk_add_f32 v[150:151], v[150:151], s[88:89] op_sel_hi:[1,0]
	v_pk_add_f32 v[152:153], v[152:153], s[88:89] op_sel_hi:[1,0]
	v_pk_add_f32 v[154:155], v[154:155], s[88:89] op_sel_hi:[1,0]
	v_pk_add_f32 v[156:157], v[156:157], s[88:89] op_sel_hi:[1,0]
	v_lshl_or_b32 v158, v153, 8, v152
	v_lshl_or_b32 v158, v158, 8, v151
	v_perm_b32 v160, v158, v150, s90
	v_lshl_or_b32 v158, v157, 8, v156
	v_lshl_or_b32 v158, v158, 8, v155
	v_perm_b32 v161, v158, v154, s90
	global_store_dwordx2 v[144:145], v[160:161], off offset:512 nt
	v_pk_mul_f32 v[162:163], v[126:127], s[84:85] op_sel_hi:[1,0]
	v_pk_mul_f32 v[164:165], v[128:129], s[84:85] op_sel_hi:[1,0]
	v_pk_mul_f32 v[166:167], v[94:95], s[84:85] op_sel_hi:[1,0]
	v_pk_mul_f32 v[168:169], v[96:97], s[84:85] op_sel_hi:[1,0]
	v_exp_f32_e32 v162, v162
	v_exp_f32_e32 v163, v163
	v_exp_f32_e32 v164, v164
	v_exp_f32_e32 v165, v165
	v_exp_f32_e32 v166, v166
	v_exp_f32_e32 v167, v167
	v_exp_f32_e32 v168, v168
	v_exp_f32_e32 v169, v169
	v_pk_fma_f32 v[162:163], v[162:163], s[86:87], s[86:87] op_sel_hi:[1,0,0]
	v_pk_fma_f32 v[164:165], v[164:165], s[86:87], s[86:87] op_sel_hi:[1,0,0]
	v_pk_fma_f32 v[166:167], v[166:167], s[86:87], s[86:87] op_sel_hi:[1,0,0]
	v_pk_fma_f32 v[168:169], v[168:169], s[86:87], s[86:87] op_sel_hi:[1,0,0]
	v_rcp_f32_e32 v162, v162
	v_rcp_f32_e32 v163, v163
	v_rcp_f32_e32 v164, v164
	v_rcp_f32_e32 v165, v165
	v_rcp_f32_e32 v166, v166
	v_rcp_f32_e32 v167, v167
	v_rcp_f32_e32 v168, v168
	v_rcp_f32_e32 v169, v169
	v_max_f32_e32 v162, 1.0, v162
	v_max_f32_e32 v163, 1.0, v163
	v_max_f32_e32 v164, 1.0, v164
	v_max_f32_e32 v165, 1.0, v165
	v_max_f32_e32 v166, 1.0, v166
	v_max_f32_e32 v167, 1.0, v167
	v_max_f32_e32 v168, 1.0, v168
	v_max_f32_e32 v169, 1.0, v169
	v_pk_add_f32 v[162:163], v[162:163], s[88:89] op_sel_hi:[1,0]
	v_pk_add_f32 v[164:165], v[164:165], s[88:89] op_sel_hi:[1,0]
	v_pk_add_f32 v[166:167], v[166:167], s[88:89] op_sel_hi:[1,0]
	v_pk_add_f32 v[168:169], v[168:169], s[88:89] op_sel_hi:[1,0]
	v_lshl_or_b32 v170, v165, 8, v164
	v_lshl_or_b32 v170, v170, 8, v163
	v_perm_b32 v172, v170, v162, s90
	v_lshl_or_b32 v170, v169, 8, v168
	v_lshl_or_b32 v170, v170, 8, v167
	v_perm_b32 v173, v170, v166, s90
	global_store_dwordx2 v[144:145], v[172:173], off offset:1536 nt
	v_pk_mul_f32 v[150:151], v[122:123], s[84:85] op_sel_hi:[1,0]
	v_pk_mul_f32 v[152:153], v[124:125], s[84:85] op_sel_hi:[1,0]
	v_pk_mul_f32 v[154:155], v[90:91], s[84:85] op_sel_hi:[1,0]
	v_pk_mul_f32 v[156:157], v[92:93], s[84:85] op_sel_hi:[1,0]
	v_exp_f32_e32 v150, v150
	v_exp_f32_e32 v151, v151
	v_exp_f32_e32 v152, v152
	v_exp_f32_e32 v153, v153
	v_exp_f32_e32 v154, v154
	v_exp_f32_e32 v155, v155
	v_exp_f32_e32 v156, v156
	v_exp_f32_e32 v157, v157
	v_pk_fma_f32 v[150:151], v[150:151], s[86:87], s[86:87] op_sel_hi:[1,0,0]
	v_pk_fma_f32 v[152:153], v[152:153], s[86:87], s[86:87] op_sel_hi:[1,0,0]
	v_pk_fma_f32 v[154:155], v[154:155], s[86:87], s[86:87] op_sel_hi:[1,0,0]
	v_pk_fma_f32 v[156:157], v[156:157], s[86:87], s[86:87] op_sel_hi:[1,0,0]
	v_rcp_f32_e32 v150, v150
	v_rcp_f32_e32 v151, v151
	v_rcp_f32_e32 v152, v152
	v_rcp_f32_e32 v153, v153
	v_rcp_f32_e32 v154, v154
	v_rcp_f32_e32 v155, v155
	v_rcp_f32_e32 v156, v156
	v_rcp_f32_e32 v157, v157
	v_max_f32_e32 v150, 1.0, v150
	v_max_f32_e32 v151, 1.0, v151
	v_max_f32_e32 v152, 1.0, v152
	v_max_f32_e32 v153, 1.0, v153
	v_max_f32_e32 v154, 1.0, v154
	v_max_f32_e32 v155, 1.0, v155
	v_max_f32_e32 v156, 1.0, v156
	v_max_f32_e32 v157, 1.0, v157
	v_pk_add_f32 v[150:151], v[150:151], s[88:89] op_sel_hi:[1,0]
	v_pk_add_f32 v[152:153], v[152:153], s[88:89] op_sel_hi:[1,0]
	v_pk_add_f32 v[154:155], v[154:155], s[88:89] op_sel_hi:[1,0]
	v_pk_add_f32 v[156:157], v[156:157], s[88:89] op_sel_hi:[1,0]
	v_lshl_or_b32 v158, v153, 8, v152
	v_lshl_or_b32 v158, v158, 8, v151
	v_perm_b32 v160, v158, v150, s90
	v_lshl_or_b32 v158, v157, 8, v156
	v_lshl_or_b32 v158, v158, 8, v155
	v_perm_b32 v161, v158, v154, s90
	global_store_dwordx2 v[144:145], v[160:161], off offset:2560 nt
	v_pk_mul_f32 v[162:163], v[118:119], s[84:85] op_sel_hi:[1,0]
	v_pk_mul_f32 v[164:165], v[120:121], s[84:85] op_sel_hi:[1,0]
	v_pk_mul_f32 v[166:167], v[86:87], s[84:85] op_sel_hi:[1,0]
	v_pk_mul_f32 v[168:169], v[88:89], s[84:85] op_sel_hi:[1,0]
	v_exp_f32_e32 v162, v162
	v_exp_f32_e32 v163, v163
	v_exp_f32_e32 v164, v164
	v_exp_f32_e32 v165, v165
	v_exp_f32_e32 v166, v166
	v_exp_f32_e32 v167, v167
	v_exp_f32_e32 v168, v168
	v_exp_f32_e32 v169, v169
	v_pk_fma_f32 v[162:163], v[162:163], s[86:87], s[86:87] op_sel_hi:[1,0,0]
	v_pk_fma_f32 v[164:165], v[164:165], s[86:87], s[86:87] op_sel_hi:[1,0,0]
	v_pk_fma_f32 v[166:167], v[166:167], s[86:87], s[86:87] op_sel_hi:[1,0,0]
	v_pk_fma_f32 v[168:169], v[168:169], s[86:87], s[86:87] op_sel_hi:[1,0,0]
	v_rcp_f32_e32 v162, v162
	v_rcp_f32_e32 v163, v163
	v_rcp_f32_e32 v164, v164
	v_rcp_f32_e32 v165, v165
	v_rcp_f32_e32 v166, v166
	v_rcp_f32_e32 v167, v167
	v_rcp_f32_e32 v168, v168
	v_rcp_f32_e32 v169, v169
	v_max_f32_e32 v162, 1.0, v162
	v_max_f32_e32 v163, 1.0, v163
	v_max_f32_e32 v164, 1.0, v164
	v_max_f32_e32 v165, 1.0, v165
	v_max_f32_e32 v166, 1.0, v166
	v_max_f32_e32 v167, 1.0, v167
	v_max_f32_e32 v168, 1.0, v168
	v_max_f32_e32 v169, 1.0, v169
	v_pk_add_f32 v[162:163], v[162:163], s[88:89] op_sel_hi:[1,0]
	v_pk_add_f32 v[164:165], v[164:165], s[88:89] op_sel_hi:[1,0]
	v_pk_add_f32 v[166:167], v[166:167], s[88:89] op_sel_hi:[1,0]
	v_pk_add_f32 v[168:169], v[168:169], s[88:89] op_sel_hi:[1,0]
	v_lshl_or_b32 v170, v165, 8, v164
	v_lshl_or_b32 v170, v170, 8, v163
	v_perm_b32 v172, v170, v162, s90
	v_lshl_or_b32 v170, v169, 8, v168
	v_lshl_or_b32 v170, v170, 8, v167
	v_perm_b32 v173, v170, v166, s90
	global_store_dwordx2 v[144:145], v[172:173], off offset:3584 nt
	s_and_b64 vcc, exec, s[0:1]
	s_cbranch_vccnz .LBB0_126
	s_mov_b64 s[2:3], 0x1000
	v_lshl_add_u64 v[146:147], v[144:145], 0, s[2:3]
	v_pk_mul_f32 v[150:151], v[38:39], s[84:85] op_sel_hi:[1,0]
	v_pk_mul_f32 v[152:153], v[40:41], s[84:85] op_sel_hi:[1,0]
	v_pk_mul_f32 v[154:155], v[6:7], s[84:85] op_sel_hi:[1,0]
	v_pk_mul_f32 v[156:157], v[8:9], s[84:85] op_sel_hi:[1,0]
	v_exp_f32_e32 v150, v150
	v_exp_f32_e32 v151, v151
	v_exp_f32_e32 v152, v152
	v_exp_f32_e32 v153, v153
	v_exp_f32_e32 v154, v154
	v_exp_f32_e32 v155, v155
	v_exp_f32_e32 v156, v156
	v_exp_f32_e32 v157, v157
	v_pk_fma_f32 v[150:151], v[150:151], s[86:87], s[86:87] op_sel_hi:[1,0,0]
	v_pk_fma_f32 v[152:153], v[152:153], s[86:87], s[86:87] op_sel_hi:[1,0,0]
	v_pk_fma_f32 v[154:155], v[154:155], s[86:87], s[86:87] op_sel_hi:[1,0,0]
	v_pk_fma_f32 v[156:157], v[156:157], s[86:87], s[86:87] op_sel_hi:[1,0,0]
	v_rcp_f32_e32 v150, v150
	v_rcp_f32_e32 v151, v151
	v_rcp_f32_e32 v152, v152
	v_rcp_f32_e32 v153, v153
	v_rcp_f32_e32 v154, v154
	v_rcp_f32_e32 v155, v155
	v_rcp_f32_e32 v156, v156
	v_rcp_f32_e32 v157, v157
	v_max_f32_e32 v150, 1.0, v150
	v_max_f32_e32 v151, 1.0, v151
	v_max_f32_e32 v152, 1.0, v152
	v_max_f32_e32 v153, 1.0, v153
	v_max_f32_e32 v154, 1.0, v154
	v_max_f32_e32 v155, 1.0, v155
	v_max_f32_e32 v156, 1.0, v156
	v_max_f32_e32 v157, 1.0, v157
	v_pk_add_f32 v[150:151], v[150:151], s[88:89] op_sel_hi:[1,0]
	v_pk_add_f32 v[152:153], v[152:153], s[88:89] op_sel_hi:[1,0]
	v_pk_add_f32 v[154:155], v[154:155], s[88:89] op_sel_hi:[1,0]
	v_pk_add_f32 v[156:157], v[156:157], s[88:89] op_sel_hi:[1,0]
	v_lshl_or_b32 v158, v153, 8, v152
	v_lshl_or_b32 v158, v158, 8, v151
	v_perm_b32 v160, v158, v150, s90
	v_lshl_or_b32 v158, v157, 8, v156
	v_lshl_or_b32 v158, v158, 8, v155
	v_perm_b32 v161, v158, v154, s90
	global_store_dwordx2 v[146:147], v[160:161], off nt
	v_pk_mul_f32 v[162:163], v[50:51], s[84:85] op_sel_hi:[1,0]
	v_pk_mul_f32 v[164:165], v[52:53], s[84:85] op_sel_hi:[1,0]
	v_pk_mul_f32 v[166:167], v[18:19], s[84:85] op_sel_hi:[1,0]
	v_pk_mul_f32 v[168:169], v[20:21], s[84:85] op_sel_hi:[1,0]
	v_exp_f32_e32 v162, v162
	v_exp_f32_e32 v163, v163
	v_exp_f32_e32 v164, v164
	v_exp_f32_e32 v165, v165
	v_exp_f32_e32 v166, v166
	v_exp_f32_e32 v167, v167
	v_exp_f32_e32 v168, v168
	v_exp_f32_e32 v169, v169
	v_pk_fma_f32 v[162:163], v[162:163], s[86:87], s[86:87] op_sel_hi:[1,0,0]
	v_pk_fma_f32 v[164:165], v[164:165], s[86:87], s[86:87] op_sel_hi:[1,0,0]
	v_pk_fma_f32 v[166:167], v[166:167], s[86:87], s[86:87] op_sel_hi:[1,0,0]
	v_pk_fma_f32 v[168:169], v[168:169], s[86:87], s[86:87] op_sel_hi:[1,0,0]
	v_rcp_f32_e32 v162, v162
	v_rcp_f32_e32 v163, v163
	v_rcp_f32_e32 v164, v164
	v_rcp_f32_e32 v165, v165
	v_rcp_f32_e32 v166, v166
	v_rcp_f32_e32 v167, v167
	v_rcp_f32_e32 v168, v168
	v_rcp_f32_e32 v169, v169
	v_max_f32_e32 v162, 1.0, v162
	v_max_f32_e32 v163, 1.0, v163
	v_max_f32_e32 v164, 1.0, v164
	v_max_f32_e32 v165, 1.0, v165
	v_max_f32_e32 v166, 1.0, v166
	v_max_f32_e32 v167, 1.0, v167
	v_max_f32_e32 v168, 1.0, v168
	v_max_f32_e32 v169, 1.0, v169
	v_pk_add_f32 v[162:163], v[162:163], s[88:89] op_sel_hi:[1,0]
	v_pk_add_f32 v[164:165], v[164:165], s[88:89] op_sel_hi:[1,0]
	v_pk_add_f32 v[166:167], v[166:167], s[88:89] op_sel_hi:[1,0]
	v_pk_add_f32 v[168:169], v[168:169], s[88:89] op_sel_hi:[1,0]
	v_lshl_or_b32 v170, v165, 8, v164
	v_lshl_or_b32 v170, v170, 8, v163
	v_perm_b32 v172, v170, v162, s90
	v_lshl_or_b32 v170, v169, 8, v168
	v_lshl_or_b32 v170, v170, 8, v167
	v_perm_b32 v173, v170, v166, s90
	global_store_dwordx2 v[146:147], v[172:173], off offset:1024 nt
	v_pk_mul_f32 v[150:151], v[46:47], s[84:85] op_sel_hi:[1,0]
	v_pk_mul_f32 v[152:153], v[48:49], s[84:85] op_sel_hi:[1,0]
	v_pk_mul_f32 v[154:155], v[14:15], s[84:85] op_sel_hi:[1,0]
	v_pk_mul_f32 v[156:157], v[16:17], s[84:85] op_sel_hi:[1,0]
	v_exp_f32_e32 v150, v150
	v_exp_f32_e32 v151, v151
	v_exp_f32_e32 v152, v152
	v_exp_f32_e32 v153, v153
	v_exp_f32_e32 v154, v154
	v_exp_f32_e32 v155, v155
	v_exp_f32_e32 v156, v156
	v_exp_f32_e32 v157, v157
	v_pk_fma_f32 v[150:151], v[150:151], s[86:87], s[86:87] op_sel_hi:[1,0,0]
	v_pk_fma_f32 v[152:153], v[152:153], s[86:87], s[86:87] op_sel_hi:[1,0,0]
	v_pk_fma_f32 v[154:155], v[154:155], s[86:87], s[86:87] op_sel_hi:[1,0,0]
	v_pk_fma_f32 v[156:157], v[156:157], s[86:87], s[86:87] op_sel_hi:[1,0,0]
	v_rcp_f32_e32 v150, v150
	v_rcp_f32_e32 v151, v151
	v_rcp_f32_e32 v152, v152
	v_rcp_f32_e32 v153, v153
	v_rcp_f32_e32 v154, v154
	v_rcp_f32_e32 v155, v155
	v_rcp_f32_e32 v156, v156
	v_rcp_f32_e32 v157, v157
	v_max_f32_e32 v150, 1.0, v150
	v_max_f32_e32 v151, 1.0, v151
	v_max_f32_e32 v152, 1.0, v152
	v_max_f32_e32 v153, 1.0, v153
	v_max_f32_e32 v154, 1.0, v154
	v_max_f32_e32 v155, 1.0, v155
	v_max_f32_e32 v156, 1.0, v156
	v_max_f32_e32 v157, 1.0, v157
	v_pk_add_f32 v[150:151], v[150:151], s[88:89] op_sel_hi:[1,0]
	v_pk_add_f32 v[152:153], v[152:153], s[88:89] op_sel_hi:[1,0]
	v_pk_add_f32 v[154:155], v[154:155], s[88:89] op_sel_hi:[1,0]
	v_pk_add_f32 v[156:157], v[156:157], s[88:89] op_sel_hi:[1,0]
	v_lshl_or_b32 v158, v153, 8, v152
	v_lshl_or_b32 v158, v158, 8, v151
	v_perm_b32 v160, v158, v150, s90
	v_lshl_or_b32 v158, v157, 8, v156
	v_lshl_or_b32 v158, v158, 8, v155
	v_perm_b32 v161, v158, v154, s90
	global_store_dwordx2 v[146:147], v[160:161], off offset:2048 nt
	v_pk_mul_f32 v[162:163], v[42:43], s[84:85] op_sel_hi:[1,0]
	v_pk_mul_f32 v[164:165], v[44:45], s[84:85] op_sel_hi:[1,0]
	v_pk_mul_f32 v[166:167], v[10:11], s[84:85] op_sel_hi:[1,0]
	v_pk_mul_f32 v[168:169], v[12:13], s[84:85] op_sel_hi:[1,0]
	v_exp_f32_e32 v162, v162
	v_exp_f32_e32 v163, v163
	v_exp_f32_e32 v164, v164
	v_exp_f32_e32 v165, v165
	v_exp_f32_e32 v166, v166
	v_exp_f32_e32 v167, v167
	v_exp_f32_e32 v168, v168
	v_exp_f32_e32 v169, v169
	v_pk_fma_f32 v[162:163], v[162:163], s[86:87], s[86:87] op_sel_hi:[1,0,0]
	v_pk_fma_f32 v[164:165], v[164:165], s[86:87], s[86:87] op_sel_hi:[1,0,0]
	v_pk_fma_f32 v[166:167], v[166:167], s[86:87], s[86:87] op_sel_hi:[1,0,0]
	v_pk_fma_f32 v[168:169], v[168:169], s[86:87], s[86:87] op_sel_hi:[1,0,0]
	v_rcp_f32_e32 v162, v162
	v_rcp_f32_e32 v163, v163
	v_rcp_f32_e32 v164, v164
	v_rcp_f32_e32 v165, v165
	v_rcp_f32_e32 v166, v166
	v_rcp_f32_e32 v167, v167
	v_rcp_f32_e32 v168, v168
	v_rcp_f32_e32 v169, v169
	v_max_f32_e32 v162, 1.0, v162
	v_max_f32_e32 v163, 1.0, v163
	v_max_f32_e32 v164, 1.0, v164
	v_max_f32_e32 v165, 1.0, v165
	v_max_f32_e32 v166, 1.0, v166
	v_max_f32_e32 v167, 1.0, v167
	v_max_f32_e32 v168, 1.0, v168
	v_max_f32_e32 v169, 1.0, v169
	v_pk_add_f32 v[162:163], v[162:163], s[88:89] op_sel_hi:[1,0]
	v_pk_add_f32 v[164:165], v[164:165], s[88:89] op_sel_hi:[1,0]
	v_pk_add_f32 v[166:167], v[166:167], s[88:89] op_sel_hi:[1,0]
	v_pk_add_f32 v[168:169], v[168:169], s[88:89] op_sel_hi:[1,0]
	v_lshl_or_b32 v170, v165, 8, v164
	v_lshl_or_b32 v170, v170, 8, v163
	v_perm_b32 v172, v170, v162, s90
	v_lshl_or_b32 v170, v169, 8, v168
	v_lshl_or_b32 v170, v170, 8, v167
	v_perm_b32 v173, v170, v166, s90
	global_store_dwordx2 v[146:147], v[172:173], off offset:3072 nt
	v_pk_mul_f32 v[150:151], v[62:63], s[84:85] op_sel_hi:[1,0]
	v_pk_mul_f32 v[152:153], v[64:65], s[84:85] op_sel_hi:[1,0]
	v_pk_mul_f32 v[154:155], v[30:31], s[84:85] op_sel_hi:[1,0]
	v_pk_mul_f32 v[156:157], v[32:33], s[84:85] op_sel_hi:[1,0]
	v_exp_f32_e32 v150, v150
	v_exp_f32_e32 v151, v151
	v_exp_f32_e32 v152, v152
	v_exp_f32_e32 v153, v153
	v_exp_f32_e32 v154, v154
	v_exp_f32_e32 v155, v155
	v_exp_f32_e32 v156, v156
	v_exp_f32_e32 v157, v157
	v_pk_fma_f32 v[150:151], v[150:151], s[86:87], s[86:87] op_sel_hi:[1,0,0]
	v_pk_fma_f32 v[152:153], v[152:153], s[86:87], s[86:87] op_sel_hi:[1,0,0]
	v_pk_fma_f32 v[154:155], v[154:155], s[86:87], s[86:87] op_sel_hi:[1,0,0]
	v_pk_fma_f32 v[156:157], v[156:157], s[86:87], s[86:87] op_sel_hi:[1,0,0]
	v_rcp_f32_e32 v150, v150
	v_rcp_f32_e32 v151, v151
	v_rcp_f32_e32 v152, v152
	v_rcp_f32_e32 v153, v153
	v_rcp_f32_e32 v154, v154
	v_rcp_f32_e32 v155, v155
	v_rcp_f32_e32 v156, v156
	v_rcp_f32_e32 v157, v157
	v_max_f32_e32 v150, 1.0, v150
	v_max_f32_e32 v151, 1.0, v151
	v_max_f32_e32 v152, 1.0, v152
	v_max_f32_e32 v153, 1.0, v153
	v_max_f32_e32 v154, 1.0, v154
	v_max_f32_e32 v155, 1.0, v155
	v_max_f32_e32 v156, 1.0, v156
	v_max_f32_e32 v157, 1.0, v157
	v_pk_add_f32 v[150:151], v[150:151], s[88:89] op_sel_hi:[1,0]
	v_pk_add_f32 v[152:153], v[152:153], s[88:89] op_sel_hi:[1,0]
	v_pk_add_f32 v[154:155], v[154:155], s[88:89] op_sel_hi:[1,0]
	v_pk_add_f32 v[156:157], v[156:157], s[88:89] op_sel_hi:[1,0]
	v_lshl_or_b32 v158, v153, 8, v152
	v_lshl_or_b32 v158, v158, 8, v151
	v_perm_b32 v160, v158, v150, s90
	v_lshl_or_b32 v158, v157, 8, v156
	v_lshl_or_b32 v158, v158, 8, v155
	v_perm_b32 v161, v158, v154, s90
	global_store_dwordx2 v[146:147], v[160:161], off offset:512 nt
	v_pk_mul_f32 v[162:163], v[66:67], s[84:85] op_sel_hi:[1,0]
	v_pk_mul_f32 v[164:165], v[68:69], s[84:85] op_sel_hi:[1,0]
	v_pk_mul_f32 v[166:167], v[34:35], s[84:85] op_sel_hi:[1,0]
	v_pk_mul_f32 v[168:169], v[36:37], s[84:85] op_sel_hi:[1,0]
	v_exp_f32_e32 v162, v162
	v_exp_f32_e32 v163, v163
	v_exp_f32_e32 v164, v164
	v_exp_f32_e32 v165, v165
	v_exp_f32_e32 v166, v166
	v_exp_f32_e32 v167, v167
	v_exp_f32_e32 v168, v168
	v_exp_f32_e32 v169, v169
	v_pk_fma_f32 v[162:163], v[162:163], s[86:87], s[86:87] op_sel_hi:[1,0,0]
	v_pk_fma_f32 v[164:165], v[164:165], s[86:87], s[86:87] op_sel_hi:[1,0,0]
	v_pk_fma_f32 v[166:167], v[166:167], s[86:87], s[86:87] op_sel_hi:[1,0,0]
	v_pk_fma_f32 v[168:169], v[168:169], s[86:87], s[86:87] op_sel_hi:[1,0,0]
	v_rcp_f32_e32 v162, v162
	v_rcp_f32_e32 v163, v163
	v_rcp_f32_e32 v164, v164
	v_rcp_f32_e32 v165, v165
	v_rcp_f32_e32 v166, v166
	v_rcp_f32_e32 v167, v167
	v_rcp_f32_e32 v168, v168
	v_rcp_f32_e32 v169, v169
	v_max_f32_e32 v162, 1.0, v162
	v_max_f32_e32 v163, 1.0, v163
	v_max_f32_e32 v164, 1.0, v164
	v_max_f32_e32 v165, 1.0, v165
	v_max_f32_e32 v166, 1.0, v166
	v_max_f32_e32 v167, 1.0, v167
	v_max_f32_e32 v168, 1.0, v168
	v_max_f32_e32 v169, 1.0, v169
	v_pk_add_f32 v[162:163], v[162:163], s[88:89] op_sel_hi:[1,0]
	v_pk_add_f32 v[164:165], v[164:165], s[88:89] op_sel_hi:[1,0]
	v_pk_add_f32 v[166:167], v[166:167], s[88:89] op_sel_hi:[1,0]
	v_pk_add_f32 v[168:169], v[168:169], s[88:89] op_sel_hi:[1,0]
	v_lshl_or_b32 v170, v165, 8, v164
	v_lshl_or_b32 v170, v170, 8, v163
	v_perm_b32 v172, v170, v162, s90
	v_lshl_or_b32 v170, v169, 8, v168
	v_lshl_or_b32 v170, v170, 8, v167
	v_perm_b32 v173, v170, v166, s90
	global_store_dwordx2 v[146:147], v[172:173], off offset:1536 nt
	v_pk_mul_f32 v[150:151], v[58:59], s[84:85] op_sel_hi:[1,0]
	v_pk_mul_f32 v[152:153], v[60:61], s[84:85] op_sel_hi:[1,0]
	v_pk_mul_f32 v[154:155], v[26:27], s[84:85] op_sel_hi:[1,0]
	v_pk_mul_f32 v[156:157], v[28:29], s[84:85] op_sel_hi:[1,0]
	v_exp_f32_e32 v150, v150
	v_exp_f32_e32 v151, v151
	v_exp_f32_e32 v152, v152
	v_exp_f32_e32 v153, v153
	v_exp_f32_e32 v154, v154
	v_exp_f32_e32 v155, v155
	v_exp_f32_e32 v156, v156
	v_exp_f32_e32 v157, v157
	v_pk_fma_f32 v[150:151], v[150:151], s[86:87], s[86:87] op_sel_hi:[1,0,0]
	v_pk_fma_f32 v[152:153], v[152:153], s[86:87], s[86:87] op_sel_hi:[1,0,0]
	v_pk_fma_f32 v[154:155], v[154:155], s[86:87], s[86:87] op_sel_hi:[1,0,0]
	v_pk_fma_f32 v[156:157], v[156:157], s[86:87], s[86:87] op_sel_hi:[1,0,0]
	v_rcp_f32_e32 v150, v150
	v_rcp_f32_e32 v151, v151
	v_rcp_f32_e32 v152, v152
	v_rcp_f32_e32 v153, v153
	v_rcp_f32_e32 v154, v154
	v_rcp_f32_e32 v155, v155
	v_rcp_f32_e32 v156, v156
	v_rcp_f32_e32 v157, v157
	v_max_f32_e32 v150, 1.0, v150
	v_max_f32_e32 v151, 1.0, v151
	v_max_f32_e32 v152, 1.0, v152
	v_max_f32_e32 v153, 1.0, v153
	v_max_f32_e32 v154, 1.0, v154
	v_max_f32_e32 v155, 1.0, v155
	v_max_f32_e32 v156, 1.0, v156
	v_max_f32_e32 v157, 1.0, v157
	v_pk_add_f32 v[150:151], v[150:151], s[88:89] op_sel_hi:[1,0]
	v_pk_add_f32 v[152:153], v[152:153], s[88:89] op_sel_hi:[1,0]
	v_pk_add_f32 v[154:155], v[154:155], s[88:89] op_sel_hi:[1,0]
	v_pk_add_f32 v[156:157], v[156:157], s[88:89] op_sel_hi:[1,0]
	v_lshl_or_b32 v158, v153, 8, v152
	v_lshl_or_b32 v158, v158, 8, v151
	v_perm_b32 v160, v158, v150, s90
	v_lshl_or_b32 v158, v157, 8, v156
	v_lshl_or_b32 v158, v158, 8, v155
	v_perm_b32 v161, v158, v154, s90
	global_store_dwordx2 v[146:147], v[160:161], off offset:2560 nt
	v_pk_mul_f32 v[162:163], v[54:55], s[84:85] op_sel_hi:[1,0]
	v_pk_mul_f32 v[164:165], v[56:57], s[84:85] op_sel_hi:[1,0]
	v_pk_mul_f32 v[166:167], v[22:23], s[84:85] op_sel_hi:[1,0]
	v_pk_mul_f32 v[168:169], v[24:25], s[84:85] op_sel_hi:[1,0]
	v_exp_f32_e32 v162, v162
	v_exp_f32_e32 v163, v163
	v_exp_f32_e32 v164, v164
	v_exp_f32_e32 v165, v165
	v_exp_f32_e32 v166, v166
	v_exp_f32_e32 v167, v167
	v_exp_f32_e32 v168, v168
	v_exp_f32_e32 v169, v169
	v_pk_fma_f32 v[162:163], v[162:163], s[86:87], s[86:87] op_sel_hi:[1,0,0]
	v_pk_fma_f32 v[164:165], v[164:165], s[86:87], s[86:87] op_sel_hi:[1,0,0]
	v_pk_fma_f32 v[166:167], v[166:167], s[86:87], s[86:87] op_sel_hi:[1,0,0]
	v_pk_fma_f32 v[168:169], v[168:169], s[86:87], s[86:87] op_sel_hi:[1,0,0]
	v_rcp_f32_e32 v162, v162
	v_rcp_f32_e32 v163, v163
	v_rcp_f32_e32 v164, v164
	v_rcp_f32_e32 v165, v165
	v_rcp_f32_e32 v166, v166
	v_rcp_f32_e32 v167, v167
	v_rcp_f32_e32 v168, v168
	v_rcp_f32_e32 v169, v169
	v_max_f32_e32 v162, 1.0, v162
	v_max_f32_e32 v163, 1.0, v163
	v_max_f32_e32 v164, 1.0, v164
	v_max_f32_e32 v165, 1.0, v165
	v_max_f32_e32 v166, 1.0, v166
	v_max_f32_e32 v167, 1.0, v167
	v_max_f32_e32 v168, 1.0, v168
	v_max_f32_e32 v169, 1.0, v169
	v_pk_add_f32 v[162:163], v[162:163], s[88:89] op_sel_hi:[1,0]
	v_pk_add_f32 v[164:165], v[164:165], s[88:89] op_sel_hi:[1,0]
	v_pk_add_f32 v[166:167], v[166:167], s[88:89] op_sel_hi:[1,0]
	v_pk_add_f32 v[168:169], v[168:169], s[88:89] op_sel_hi:[1,0]
	v_lshl_or_b32 v170, v165, 8, v164
	v_lshl_or_b32 v170, v170, 8, v163
	v_perm_b32 v172, v170, v162, s90
	v_lshl_or_b32 v170, v169, 8, v168
	v_lshl_or_b32 v170, v170, 8, v167
	v_perm_b32 v173, v170, v166, s90
	global_store_dwordx2 v[146:147], v[172:173], off offset:3584 nt
	s_branch .LBB0_126

.LBB0_167:
	s_andn2_b64 vcc, exec, s[8:9]
	s_cbranch_vccnz .LBB0_94
	s_barrier
	s_branch .LBB0_94
.LBB0_170:
	s_waitcnt vmcnt(0)
	v_readlane_b32 s60, v254, 24
	v_readlane_b32 s66, v254, 26
	v_readlane_b32 s56, v254, 29
	v_readlane_b32 s61, v254, 25
	v_readlane_b32 s67, v254, 27
	v_readlane_b32 s62, v254, 28
	v_readlane_b32 s57, v254, 30
	v_readlane_b32 s58, v254, 31
	v_readlane_b32 s64, v254, 33
	v_readlane_b32 s52, v254, 35
	v_readlane_b32 s54, v254, 34
	s_barrier
	v_readlane_b32 s59, v254, 32
	v_readlane_b32 s53, v254, 36
